# MLA norm2: next row's five loads prefetched into registers at the top of each row iteration
# speedup vs baseline: 1.0103x; 1.0026x over previous
.LBB0_1449:
	s_or_b64 exec, exec, s[0:1]
	s_waitcnt lgkmcnt(0)
	v_mov_b32_e32 v2, v0
	s_barrier
	v_readlane_b32 s0, v252, 57
	v_lshrrev_b32_e32 v42, 6, v2
	v_mov_b32_e32 v43, v0
	v_add_u32_e32 v58, s0, v42
	s_mov_b32 s0, 0x8400
	v_cmp_gt_i32_e32 vcc, s0, v58
	s_and_saveexec_b64 s[2:3], vcc
	s_cbranch_execz .LBB0_1456
	v_readlane_b32 s4, v251, 42
	v_readlane_b32 s8, v251, 46
	v_readlane_b32 s9, v251, 47
	v_readlane_b32 s10, v251, 48
	v_readlane_b32 s11, v251, 49
	v_readlane_b32 s12, v251, 50
	v_readlane_b32 s13, v251, 51
	v_readlane_b32 s14, v251, 52
	v_readlane_b32 s15, v251, 53
	v_and_b32_e32 v60, 3, v43
	v_readlane_b32 s16, v251, 54
	v_readlane_b32 s17, v251, 55
	v_readlane_b32 s18, v251, 56
	v_readlane_b32 s19, v251, 57
	s_mov_b64 s[8:9], s[12:13]
	v_lshlrev_b32_e32 v30, 6, v60
	s_mov_b64 s[10:11], s[14:15]
	s_mov_b64 s[12:13], s[16:17]
	s_mov_b64 s[14:15], s[18:19]
	global_load_dwordx4 v[2:5], v30, s[10:11]
	global_load_dwordx4 v[6:9], v30, s[14:15]
	global_load_dwordx4 v[10:13], v30, s[10:11] offset:16
	global_load_dwordx4 v[14:17], v30, s[14:15] offset:16
	global_load_dwordx4 v[18:21], v30, s[10:11] offset:32
	global_load_dwordx4 v[22:25], v30, s[14:15] offset:32
	global_load_dwordx4 v[26:29], v30, s[10:11] offset:48
	s_nop 0
	global_load_dwordx4 v[30:33], v30, s[14:15] offset:48
	v_lshlrev_b32_e32 v62, 5, v60
	global_load_dwordx4 v[34:37], v62, s[12:13]
	global_load_dwordx4 v[38:41], v62, s[12:13] offset:16
	v_lshlrev_b32_e32 v44, 3, v43
	v_and_b32_e32 v44, 8, v44
	v_cvt_f32_ubyte0_e32 v45, v44
	v_or_b32_e32 v48, 1, v44
	v_mul_f32_e32 v46, 0xbf549a78, v45
	s_mov_b32 s4, 0xc2fc0000
	v_cvt_f32_ubyte0_e32 v48, v48
	v_mov_b32_e32 v47, 0x42800000
	v_cmp_gt_f32_e32 vcc, s4, v46
	v_mul_f32_e32 v49, 0xbf549a78, v48
	v_cmp_gt_f32_e64 s[0:1], s4, v49
	v_cndmask_b32_e32 v46, 0, v47, vcc
	v_fmac_f32_e32 v46, 0xbf549a78, v45
	v_cndmask_b32_e64 v49, 0, v47, s[0:1]
	v_exp_f32_e32 v45, v46
	v_fmac_f32_e32 v49, 0xbf549a78, v48
	v_exp_f32_e32 v48, v49
	v_not_b32_e32 v46, 63
	v_cndmask_b32_e32 v49, 0, v46, vcc
	v_ldexp_f32 v82, v45, v49
	v_cndmask_b32_e64 v45, 0, v46, s[0:1]
	v_ldexp_f32 v83, v48, v45
	v_or_b32_e32 v45, 2, v44
	v_cvt_f32_ubyte0_e32 v45, v45
	v_mul_f32_e32 v48, 0xbf549a78, v45
	v_cmp_gt_f32_e32 vcc, s4, v48
	v_bfe_u32 v90, v43, 2, 4
	v_mov_b32_e32 v65, 0
	v_cndmask_b32_e32 v48, 0, v47, vcc
	v_fmac_f32_e32 v48, 0xbf549a78, v45
	v_exp_f32_e32 v45, v48
	v_or_b32_e32 v48, 3, v44
	v_cvt_f32_ubyte0_e32 v48, v48
	v_mul_f32_e32 v49, 0xbf549a78, v48
	v_cmp_gt_f32_e64 s[0:1], s4, v49
	v_ashrrev_i32_e32 v59, 31, v58
	v_readlane_b32 s5, v251, 43
	v_cndmask_b32_e64 v49, 0, v47, s[0:1]
	v_fmac_f32_e32 v49, 0xbf549a78, v48
	v_exp_f32_e32 v48, v49
	v_cndmask_b32_e32 v49, 0, v46, vcc
	v_ldexp_f32 v84, v45, v49
	v_cndmask_b32_e64 v45, 0, v46, s[0:1]
	v_ldexp_f32 v85, v48, v45
	v_or_b32_e32 v45, 4, v44
	v_cvt_f32_ubyte0_e32 v45, v45
	v_mul_f32_e32 v48, 0xbf549a78, v45
	v_cmp_gt_f32_e32 vcc, s4, v48
	v_readlane_b32 s6, v251, 44
	v_readlane_b32 s7, v251, 45
	v_cndmask_b32_e32 v48, 0, v47, vcc
	v_fmac_f32_e32 v48, 0xbf549a78, v45
	v_exp_f32_e32 v45, v48
	v_or_b32_e32 v48, 5, v44
	v_cvt_f32_ubyte0_e32 v48, v48
	v_mul_f32_e32 v49, 0xbf549a78, v48
	v_cmp_gt_f32_e64 s[0:1], s4, v49
	s_ashr_i32 s61, s60, 31
	v_mov_b32_e32 v61, v65
	v_cndmask_b32_e64 v49, 0, v47, s[0:1]
	v_fmac_f32_e32 v49, 0xbf549a78, v48
	v_exp_f32_e32 v48, v49
	v_cndmask_b32_e32 v49, 0, v46, vcc
	v_ldexp_f32 v86, v45, v49
	v_cndmask_b32_e64 v45, 0, v46, s[0:1]
	v_ldexp_f32 v87, v48, v45
	v_or_b32_e32 v45, 6, v44
	v_cvt_f32_ubyte0_e32 v45, v45
	v_mul_f32_e32 v48, 0xbf549a78, v45
	v_cmp_gt_f32_e32 vcc, s4, v48
	v_or_b32_e32 v44, 7, v44
	v_cvt_f32_ubyte0_e32 v44, v44
	v_cndmask_b32_e32 v48, 0, v47, vcc
	v_fmac_f32_e32 v48, 0xbf549a78, v45
	v_exp_f32_e32 v45, v48
	v_mul_f32_e32 v48, 0xbf549a78, v44
	v_cmp_gt_f32_e64 s[0:1], s4, v48
	v_cmp_gt_u32_e64 s[6:7], 2, v60
	v_mov_b32_e32 v67, v65
	v_cndmask_b32_e64 v47, 0, v47, s[0:1]
	v_fmac_f32_e32 v47, 0xbf549a78, v44
	v_exp_f32_e32 v44, v47
	v_cndmask_b32_e32 v47, 0, v46, vcc
	v_ldexp_f32 v88, v45, v47
	v_cndmask_b32_e64 v45, 0, v46, s[0:1]
	v_ldexp_f32 v89, v44, v45
	v_mbcnt_hi_u32_b32 v45, -1, v1
	v_and_b32_e32 v47, 64, v45
	v_xor_b32_e32 v46, 1, v45
	v_add_u32_e32 v47, 64, v47
	v_cmp_lt_i32_e32 vcc, v46, v47
	v_mul_u32_u24_e32 v44, 0x60, v90
	v_readlane_b32 s0, v253, 28
	v_cndmask_b32_e32 v46, v45, v46, vcc
	v_lshlrev_b32_e32 v91, 2, v46
	v_xor_b32_e32 v46, 2, v45
	v_cmp_lt_i32_e32 vcc, v46, v47
	v_readlane_b32 s1, v253, 29
	s_lshl_b32 s4, s0, 4
	v_cndmask_b32_e32 v45, v45, v46, vcc
	v_lshlrev_b32_e32 v92, 2, v45
	v_bfe_u32 v45, v43, 1, 1
	v_lshlrev_b32_e32 v43, 7, v43
	v_or_b32_e32 v66, 4, v45
	v_mov_b32_e32 v45, 0x2000
	v_and_b32_e32 v64, 0x80, v43
	v_and_or_b32 v93, v42, 7, v45
	v_lshl_add_u64 v[68:69], s[50:51], 0, v[64:65]
	v_lshlrev_b32_e32 v64, 1, v44
	v_lshlrev_b64 v[44:45], 11, v[58:59]
	v_lshlrev_b32_e32 v46, 7, v90
	v_or_b32_e32 v44, v44, v46
	v_lshl_add_u64 v[44:45], s[44:45], 0, v[44:45]
	v_lshl_add_u64 v[72:73], v[44:45], 0, 16
	v_mov_b32_e32 v44, 0x80
	v_lshlrev_b32_e32 v43, 1, v42
	v_lshl_or_b32 v74, v60, 4, v44
	v_lshlrev_b64 v[44:45], 12, v[58:59]
	v_lshl_add_u32 v43, s96, 4, v43
	v_lshlrev_b32_e32 v42, 3, v42
	s_lshl_b32 s5, s0, 6
	s_movk_i32 s0, 0xc00
	v_or_b32_e32 v44, v44, v46
	v_add_u32_e32 v94, 0x7fff0000, v43
	v_lshl_add_u32 v95, s96, 6, v42
	v_mad_i64_i32 v[42:43], s[0:1], v58, s0, v[64:65]
	v_lshl_add_u64 v[44:45], s[40:41], 0, v[44:45]
	v_mov_b32_e32 v63, v65
	v_lshl_add_u64 v[70:71], s[42:43], 0, v[42:43]
	s_mul_hi_i32 s11, s60, 0xc00
	s_mul_i32 s10, s60, 0xc00
	s_lshl_b64 s[12:13], s[60:61], 11
	v_mov_b32_e32 v75, v65
	v_lshl_add_u64 v[76:77], v[44:45], 0, 16
	s_lshl_b64 s[14:15], s[60:61], 12
	v_lshl_add_u64 v[78:79], s[38:39], 0, v[42:43]
	s_mov_b64 s[16:17], 0
	v_mov_b32_e32 v59, 0x358637bd
	s_mov_b32 s18, 0xf800000
	v_mov_b32_e32 v96, 0x260
	v_lshl_add_u64 v[132:133], v[78:79], 0, v[62:63]
	global_load_dwordx4 v[100:103], v[132:133], off offset:16
	global_load_dwordx4 v[104:107], v[132:133], off
	v_lshl_add_u64 v[132:133], v[78:79], 0, v[74:75]
	global_load_dwordx4 v[108:111], v[132:133], off
	v_lshl_add_u64 v[132:133], v[76:77], 0, v[62:63]
	global_load_dwordx4 v[112:115], v[132:133], off
	global_load_dwordx4 v[116:119], v[132:133], off offset:-16
	s_waitcnt vmcnt(0)
	s_branch .LBB0_1452
.LBB0_1451:
	s_or_b64 exec, exec, s[0:1]
	s_nop 1
	v_mov_b32_e32 v42, v124
	v_mov_b32_e32 v43, v125
	v_mov_b32_e32 v44, v126
	v_mov_b32_e32 v45, v127
	v_mov_b32_e32 v46, v128
	v_mov_b32_e32 v47, v129
	v_mov_b32_e32 v48, v130
	v_mov_b32_e32 v49, v131
	v_add_u32_e32 v58, s60, v58
	v_add_u32_e32 v94, s4, v94
	v_add_u32_e32 v95, s5, v95
	v_lshl_add_u64 v[70:71], v[70:71], 0, s[10:11]
	v_lshl_add_u64 v[76:77], v[76:77], 0, s[14:15]
	v_lshl_add_u64 v[78:79], v[78:79], 0, s[10:11]
	v_lshlrev_b32_e32 v81, 16, v44
	v_lshlrev_b32_e32 v52, 16, v46
	v_and_b32_e32 v46, 0xffff0000, v46
	v_and_b32_e32 v97, 0xffff0000, v44
	v_mul_f32_e32 v44, v46, v46
	v_lshlrev_b32_e32 v53, 16, v47
	v_fmac_f32_e32 v44, v52, v52
	v_and_b32_e32 v47, 0xffff0000, v47
	v_fmac_f32_e32 v44, v53, v53
	v_lshlrev_b32_e32 v54, 16, v48
	v_fmac_f32_e32 v44, v47, v47
	v_and_b32_e32 v48, 0xffff0000, v48
	v_fmac_f32_e32 v44, v54, v54
	v_lshlrev_b32_e32 v55, 16, v49
	v_fmac_f32_e32 v44, v48, v48
	v_and_b32_e32 v49, 0xffff0000, v49
	v_fmac_f32_e32 v44, v55, v55
	v_lshlrev_b32_e32 v56, 16, v42
	v_fmac_f32_e32 v44, v49, v49
	v_and_b32_e32 v57, 0xffff0000, v42
	v_fmac_f32_e32 v44, v56, v56
	v_lshlrev_b32_e32 v64, 16, v43
	v_fmac_f32_e32 v44, v57, v57
	v_and_b32_e32 v80, 0xffff0000, v43
	v_fmac_f32_e32 v44, v64, v64
	v_fmac_f32_e32 v44, v80, v80
	v_fmac_f32_e32 v44, v81, v81
	v_and_b32_e32 v50, 0xffff0000, v45
	v_lshlrev_b32_e32 v51, 16, v45
	v_fmac_f32_e32 v44, v97, v97
	v_pk_mul_f32 v[42:43], v[50:51], v[50:51]
	s_nop 0
	v_add_f32_e32 v43, v43, v44
	v_add_f32_e32 v42, v42, v43
	ds_bpermute_b32 v43, v91, v42
	s_waitcnt lgkmcnt(0)
	v_add_f32_e32 v42, v42, v43
	ds_bpermute_b32 v43, v92, v42
	s_waitcnt lgkmcnt(0)
	v_add_f32_e32 v42, v42, v43
	v_fmamk_f32 v42, v42, 0x3c800000, v59
	v_cmp_gt_f32_e32 vcc, s18, v42
	v_mul_f32_e32 v43, 0x4f800000, v42
	s_nop 0
	v_cndmask_b32_e32 v42, v42, v43, vcc
	v_sqrt_f32_e32 v43, v42
	s_nop 0
	v_add_u32_e32 v44, -1, v43
	v_fma_f32 v45, -v44, v43, v42
	v_cmp_ge_f32_e64 s[0:1], 0, v45
	v_add_u32_e32 v45, 1, v43
	s_nop 0
	v_cndmask_b32_e64 v44, v43, v44, s[0:1]
	v_fma_f32 v43, -v45, v43, v42
	v_cmp_lt_f32_e64 s[0:1], 0, v43
	s_nop 1
	v_cndmask_b32_e64 v43, v44, v45, s[0:1]
	v_mul_f32_e32 v44, 0x37800000, v43
	v_cndmask_b32_e32 v43, v43, v44, vcc
	v_cmp_class_f32_e32 vcc, v42, v96
	s_nop 1
	v_cndmask_b32_e32 v42, v43, v42, vcc
	v_div_scale_f32 v43, s[0:1], v42, v42, 1.0
	v_rcp_f32_e32 v44, v43
	s_mov_b32 s0, 0x83ff
	v_fma_f32 v45, -v43, v44, 1.0
	v_fmac_f32_e32 v44, v45, v44
	v_div_scale_f32 v45, vcc, 1.0, v42, 1.0
	v_mul_f32_e32 v98, v45, v44
	v_fma_f32 v99, -v43, v98, v45
	v_fmac_f32_e32 v98, v99, v44
	v_fma_f32 v43, -v43, v98, v45
	v_div_fmas_f32 v43, v43, v44, v98
	v_div_fixup_f32 v98, v43, v42, 1.0
	v_mul_f32_e32 v42, v98, v52
	v_mul_f32_e32 v43, v98, v46
	v_mul_f32_e32 v42, v6, v42
	v_mul_f32_e32 v43, v7, v43
	v_cvt_pk_bf16_f32 v42, v42, v43
	v_mul_f32_e32 v43, v98, v53
	v_mul_f32_e32 v44, v98, v47
	v_mul_f32_e32 v43, v8, v43
	v_mul_f32_e32 v44, v9, v44
	v_cvt_pk_bf16_f32 v43, v43, v44
	v_mul_f32_e32 v44, v98, v54
	v_mul_f32_e32 v45, v98, v48
	v_mul_f32_e32 v44, v14, v44
	v_mul_f32_e32 v45, v15, v45
	v_cvt_pk_bf16_f32 v44, v44, v45
	v_mul_f32_e32 v45, v98, v55
	v_mul_f32_e32 v46, v98, v49
	v_mul_f32_e32 v45, v16, v45
	v_mul_f32_e32 v46, v17, v46
	v_cvt_pk_bf16_f32 v45, v45, v46
	v_mul_f32_e32 v46, v98, v56
	v_mul_f32_e32 v47, v98, v57
	v_mul_f32_e32 v46, v22, v46
	v_mul_f32_e32 v47, v23, v47
	v_cvt_pk_bf16_f32 v46, v46, v47
	v_mul_f32_e32 v47, v98, v64
	v_mul_f32_e32 v48, v98, v80
	v_mul_f32_e32 v47, v24, v47
	v_mul_f32_e32 v48, v25, v48
	v_cvt_pk_bf16_f32 v47, v47, v48
	v_mul_f32_e32 v48, v98, v81
	v_mul_f32_e32 v49, v98, v97
	v_mul_f32_e32 v48, v30, v48
	v_mul_f32_e32 v49, v31, v49
	v_cvt_pk_bf16_f32 v48, v48, v49
	v_mul_f32_e32 v49, v98, v51
	v_mul_f32_e32 v50, v98, v50
	v_mul_f32_e32 v49, v32, v49
	v_mul_f32_e32 v50, v33, v50
	v_cmp_lt_i32_e32 vcc, s0, v58
	v_cvt_pk_bf16_f32 v49, v49, v50
	v_lshl_add_u64 v[50:51], v[72:73], 0, v[62:63]
	v_lshl_add_u64 v[72:73], v[72:73], 0, s[12:13]
	s_or_b64 s[16:17], vcc, s[16:17]
	global_store_dwordx4 v[50:51], v[42:45], off offset:-16
	global_store_dwordx4 v[50:51], v[46:49], off
	s_andn2_b64 exec, exec, s[16:17]
	s_cbranch_execz .LBB0_1456
.LBB0_1452:
	s_waitcnt vmcnt(5)
	v_mov_b32_e32 v42, v100
	v_mov_b32_e32 v43, v101
	v_mov_b32_e32 v44, v102
	v_mov_b32_e32 v45, v103
	v_mov_b32_e32 v46, v104
	v_mov_b32_e32 v47, v105
	v_mov_b32_e32 v48, v106
	v_mov_b32_e32 v49, v107
	v_mov_b32_e32 v120, v108
	v_mov_b32_e32 v121, v109
	v_mov_b32_e32 v122, v110
	v_mov_b32_e32 v123, v111
	v_mov_b32_e32 v124, v112
	v_mov_b32_e32 v125, v113
	v_mov_b32_e32 v126, v114
	v_mov_b32_e32 v127, v115
	v_mov_b32_e32 v128, v116
	v_mov_b32_e32 v129, v117
	v_mov_b32_e32 v130, v118
	v_mov_b32_e32 v131, v119
	v_lshl_add_u64 v[134:135], v[78:79], 0, s[10:11]
	v_lshl_add_u64 v[136:137], v[76:77], 0, s[14:15]
	v_lshl_add_u64 v[132:133], v[134:135], 0, v[62:63]
	global_load_dwordx4 v[100:103], v[132:133], off offset:16
	global_load_dwordx4 v[104:107], v[132:133], off
	v_lshl_add_u64 v[132:133], v[134:135], 0, v[74:75]
	global_load_dwordx4 v[108:111], v[132:133], off
	v_lshl_add_u64 v[132:133], v[136:137], 0, v[62:63]
	global_load_dwordx4 v[112:115], v[132:133], off
	global_load_dwordx4 v[116:119], v[132:133], off offset:-16
	v_lshlrev_b32_e32 v97, 16, v44
	v_lshlrev_b32_e32 v50, 16, v46
	v_and_b32_e32 v46, 0xffff0000, v46
	v_and_b32_e32 v98, 0xffff0000, v44
	v_mul_f32_e32 v44, v46, v46
	v_lshlrev_b32_e32 v51, 16, v47
	v_fmac_f32_e32 v44, v50, v50
	v_and_b32_e32 v47, 0xffff0000, v47
	v_fmac_f32_e32 v44, v51, v51
	v_lshlrev_b32_e32 v52, 16, v48
	v_fmac_f32_e32 v44, v47, v47
	v_and_b32_e32 v48, 0xffff0000, v48
	v_fmac_f32_e32 v44, v52, v52
	v_lshlrev_b32_e32 v54, 16, v49
	v_fmac_f32_e32 v44, v48, v48
	v_and_b32_e32 v49, 0xffff0000, v49
	v_fmac_f32_e32 v44, v54, v54
	v_lshlrev_b32_e32 v55, 16, v42
	v_fmac_f32_e32 v44, v49, v49
	v_and_b32_e32 v56, 0xffff0000, v42
	v_fmac_f32_e32 v44, v55, v55
	v_lshlrev_b32_e32 v57, 16, v43
	v_fmac_f32_e32 v44, v56, v56
	v_and_b32_e32 v64, 0xffff0000, v43
	v_fmac_f32_e32 v44, v57, v57
	v_fmac_f32_e32 v44, v64, v64
	v_fmac_f32_e32 v44, v97, v97
	v_and_b32_e32 v80, 0xffff0000, v45
	v_lshlrev_b32_e32 v81, 16, v45
	v_fmac_f32_e32 v44, v98, v98
	v_pk_mul_f32 v[42:43], v[80:81], v[80:81]
	s_nop 0
	v_add_f32_e32 v43, v43, v44
	v_add_f32_e32 v42, v42, v43
	ds_bpermute_b32 v43, v91, v42
	s_waitcnt lgkmcnt(0)
	v_add_f32_e32 v42, v42, v43
	ds_bpermute_b32 v43, v92, v42
	s_waitcnt lgkmcnt(0)
	v_add_f32_e32 v42, v42, v43
	v_fmamk_f32 v42, v42, 0x3c800000, v59
	v_cmp_gt_f32_e32 vcc, s18, v42
	v_mul_f32_e32 v43, 0x4f800000, v42
	s_nop 0
	v_cndmask_b32_e32 v42, v42, v43, vcc
	v_sqrt_f32_e32 v43, v42
	s_nop 0
	v_add_u32_e32 v44, -1, v43
	v_fma_f32 v45, -v44, v43, v42
	v_cmp_ge_f32_e64 s[0:1], 0, v45
	v_add_u32_e32 v45, 1, v43
	s_nop 0
	v_cndmask_b32_e64 v44, v43, v44, s[0:1]
	v_fma_f32 v43, -v45, v43, v42
	v_cmp_lt_f32_e64 s[0:1], 0, v43
	s_nop 1
	v_cndmask_b32_e64 v43, v44, v45, s[0:1]
	v_mul_f32_e32 v44, 0x37800000, v43
	v_cndmask_b32_e32 v43, v43, v44, vcc
	v_cmp_class_f32_e32 vcc, v42, v96
	s_nop 1
	v_cndmask_b32_e32 v42, v43, v42, vcc
	v_div_scale_f32 v43, s[0:1], v42, v42, 1.0
	v_rcp_f32_e32 v44, v43
	s_movk_i32 s0, 0x7fff
	v_cmp_lt_i32_e64 s[8:9], s0, v58
	s_mov_b32 s0, 0x7ffffff0
	v_fma_f32 v45, -v43, v44, 1.0
	v_fmac_f32_e32 v44, v45, v44
	v_div_scale_f32 v45, vcc, 1.0, v42, 1.0
	v_mul_f32_e32 v53, v45, v44
	v_fma_f32 v99, -v43, v53, v45
	v_fmac_f32_e32 v53, v99, v44
	v_fma_f32 v43, -v43, v53, v45
	v_div_fmas_f32 v43, v43, v44, v53
	v_div_fixup_f32 v53, v43, v42, 1.0
	v_mul_f32_e32 v42, v53, v50
	v_mul_f32_e32 v43, v53, v46
	v_mul_f32_e32 v42, v2, v42
	v_mul_f32_e32 v43, v3, v43
	v_mul_f32_e32 v42, 0x3e16c740, v42
	v_mul_f32_e32 v43, 0x3e16c740, v43
	v_cvt_pk_bf16_f32 v46, v42, v43
	v_mul_f32_e32 v42, v6, v42
	v_mul_f32_e32 v43, v7, v43
	v_cvt_pk_bf16_f32 v42, v42, v43
	v_mul_f32_e32 v43, v53, v51
	v_mul_f32_e32 v44, v53, v47
	v_mul_f32_e32 v43, v4, v43
	v_mul_f32_e32 v44, v5, v44
	v_mul_f32_e32 v43, 0x3e16c740, v43
	v_mul_f32_e32 v44, 0x3e16c740, v44
	v_cvt_pk_bf16_f32 v47, v43, v44
	v_mul_f32_e32 v43, v8, v43
	v_mul_f32_e32 v44, v9, v44
	v_cvt_pk_bf16_f32 v43, v43, v44
	v_mul_f32_e32 v44, v53, v52
	v_mul_f32_e32 v45, v53, v48
	v_mul_f32_e32 v44, v10, v44
	v_mul_f32_e32 v45, v11, v45
	v_mul_f32_e32 v44, 0x3e16c740, v44
	v_mul_f32_e32 v45, 0x3e16c740, v45
	v_cvt_pk_bf16_f32 v48, v44, v45
	v_mul_f32_e32 v44, v14, v44
	v_mul_f32_e32 v45, v15, v45
	v_cvt_pk_bf16_f32 v50, v44, v45
	v_mul_f32_e32 v44, v53, v54
	v_mul_f32_e32 v45, v53, v49
	v_mul_f32_e32 v44, v12, v44
	v_mul_f32_e32 v45, v13, v45
	v_mul_f32_e32 v44, 0x3e16c740, v44
	v_mul_f32_e32 v45, 0x3e16c740, v45
	v_cvt_pk_bf16_f32 v49, v44, v45
	v_mul_f32_e32 v44, v16, v44
	v_mul_f32_e32 v45, v17, v45
	v_cvt_pk_bf16_f32 v51, v44, v45
	v_mul_f32_e32 v44, v53, v55
	v_mul_f32_e32 v45, v53, v56
	v_mul_f32_e32 v44, v18, v44
	v_mul_f32_e32 v45, v19, v45
	v_mul_f32_e32 v44, 0x3e16c740, v44
	v_mul_f32_e32 v45, 0x3e16c740, v45
	v_cvt_pk_bf16_f32 v54, v44, v45
	v_mul_f32_e32 v44, v22, v44
	v_mul_f32_e32 v45, v23, v45
	v_cvt_pk_bf16_f32 v44, v44, v45
	v_mul_f32_e32 v45, v53, v57
	v_mul_f32_e32 v52, v53, v64
	v_mul_f32_e32 v45, v20, v45
	v_mul_f32_e32 v52, v21, v52
	v_mul_f32_e32 v45, 0x3e16c740, v45
	v_mul_f32_e32 v52, 0x3e16c740, v52
	v_cvt_pk_bf16_f32 v55, v45, v52
	v_mul_f32_e32 v45, v24, v45
	v_mul_f32_e32 v52, v25, v52
	v_cvt_pk_bf16_f32 v45, v45, v52
	v_mul_f32_e32 v52, v53, v97
	v_mul_f32_e32 v56, v53, v98
	v_mul_f32_e32 v52, v26, v52
	v_mul_f32_e32 v56, v27, v56
	v_mul_f32_e32 v52, 0x3e16c740, v52
	v_mul_f32_e32 v57, 0x3e16c740, v56
	v_cvt_pk_bf16_f32 v56, v52, v57
	v_mul_f32_e32 v52, v30, v52
	v_mul_f32_e32 v57, v31, v57
	v_cvt_pk_bf16_f32 v52, v52, v57
	v_mul_f32_e32 v57, v53, v81
	v_mul_f32_e32 v53, v53, v80
	v_mul_f32_e32 v53, v29, v53
	v_mul_f32_e32 v57, v28, v57
	v_mul_f32_e32 v53, 0x3e16c740, v53
	v_mul_f32_e32 v64, 0x3e16c740, v57
	v_cvt_pk_bf16_f32 v57, v64, v53
	v_mul_f32_e32 v53, v33, v53
	v_lshl_add_u64 v[80:81], v[70:71], 0, v[62:63]
	v_mul_f32_e32 v64, v32, v64
	v_cvt_pk_bf16_f32 v53, v64, v53
	global_store_dwordx4 v[80:81], v[46:49], off
	global_store_dwordx4 v[80:81], v[54:57], off offset:16
	s_nop 0
	v_and_b32_e32 v47, 56, v95
	v_and_or_b32 v46, v94, s0, v90
	v_lshlrev_b32_e32 v64, 1, v47
	s_and_saveexec_b64 s[0:1], s[8:9]
	s_cbranch_execz .LBB0_1454
	v_mad_u64_u32 v[48:49], s[20:21], v46, 6, v[60:61]
	v_lshlrev_b64 v[48:49], 8, v[48:49]
	v_lshl_add_u64 v[48:49], s[50:51], 0, v[48:49]
	v_lshl_add_u64 v[48:49], v[48:49], 0, v[64:65]
	global_store_dwordx4 v[48:49], v[42:45], off
	global_store_dwordx4 v[48:49], v[50:53], off offset:128
.LBB0_1454:
	s_or_b64 exec, exec, s[0:1]
	v_mov_b32_e32 v42, v120
	v_mov_b32_e32 v43, v121
	v_mov_b32_e32 v44, v122
	v_mov_b32_e32 v45, v123
	v_and_b32_e32 v48, 0xffff0000, v42
	v_lshlrev_b32_e32 v47, 16, v42
	v_lshlrev_b32_e32 v51, 16, v44
	v_and_b32_e32 v52, 0xffff0000, v44
	v_mul_f32_e32 v44, v48, v48
	v_lshlrev_b32_e32 v49, 16, v43
	v_fmac_f32_e32 v44, v47, v47
	v_and_b32_e32 v50, 0xffff0000, v43
	v_fmac_f32_e32 v44, v49, v49
	v_fmac_f32_e32 v44, v50, v50
	v_fmac_f32_e32 v44, v51, v51
	v_lshlrev_b32_e32 v43, 16, v45
	v_fmac_f32_e32 v44, v52, v52
	v_and_b32_e32 v42, 0xffff0000, v45
	v_fmac_f32_e32 v44, v43, v43
	v_fmac_f32_e32 v44, v42, v42
	ds_bpermute_b32 v45, v91, v44
	s_waitcnt lgkmcnt(0)
	v_add_f32_e32 v44, v44, v45
	ds_bpermute_b32 v45, v92, v44
	s_waitcnt lgkmcnt(0)
	v_add_f32_e32 v44, v44, v45
	v_fmamk_f32 v44, v44, 0x3d000000, v59
	v_cmp_gt_f32_e32 vcc, s18, v44
	v_mul_f32_e32 v45, 0x4f800000, v44
	s_nop 0
	v_cndmask_b32_e32 v44, v44, v45, vcc
	v_sqrt_f32_e32 v45, v44
	s_nop 0
	v_add_u32_e32 v53, -1, v45
	v_fma_f32 v54, -v53, v45, v44
	v_cmp_ge_f32_e64 s[0:1], 0, v54
	v_add_u32_e32 v54, 1, v45
	s_nop 0
	v_cndmask_b32_e64 v53, v45, v53, s[0:1]
	v_fma_f32 v45, -v54, v45, v44
	v_cmp_lt_f32_e64 s[0:1], 0, v45
	s_nop 1
	v_cndmask_b32_e64 v45, v53, v54, s[0:1]
	v_mul_f32_e32 v53, 0x37800000, v45
	v_cndmask_b32_e32 v45, v45, v53, vcc
	v_cmp_class_f32_e32 vcc, v44, v96
	s_nop 1
	v_cndmask_b32_e32 v44, v45, v44, vcc
	v_div_scale_f32 v45, s[0:1], v44, v44, 1.0
	v_rcp_f32_e32 v53, v45
	s_mov_b32 s0, 0x8000
	v_fma_f32 v54, -v45, v53, 1.0
	v_fmac_f32_e32 v53, v54, v53
	v_div_scale_f32 v54, vcc, 1.0, v44, 1.0
	v_mul_f32_e32 v55, v54, v53
	v_fma_f32 v56, -v45, v55, v54
	v_fmac_f32_e32 v55, v56, v53
	v_fma_f32 v45, -v45, v55, v54
	v_div_fmas_f32 v45, v45, v53, v55
	v_div_fixup_f32 v44, v45, v44, 1.0
	v_ashrrev_i32_e32 v45, 31, v58
	v_lshrrev_b32_e32 v45, 21, v45
	v_add_u32_e32 v45, v58, v45
	v_and_b32_e32 v45, 0xfffff800, v45
	v_cmp_gt_i32_e32 vcc, s0, v58
	v_sub_u32_e32 v45, v58, v45
	v_mul_f32_e32 v47, v44, v47
	v_cndmask_b32_e32 v45, v93, v45, vcc
	v_mul_f32_e32 v53, v34, v47
	v_cvt_f32_i32_e32 v47, v45
	ds_bpermute_b32 v54, v92, v53
	v_mul_f32_e32 v48, v44, v48
	v_mul_f32_e32 v49, v44, v49
	v_mul_f32_e32 v45, v82, v47
	v_mul_f32_e32 v55, 0.15915494, v45
	v_rndne_f32_e32 v55, v55
	v_fmac_f32_e32 v45, 0xc0c90000, v55
	v_fmac_f32_e32 v45, 0xbafdaa22, v55
	v_mul_f32_e32 v45, 0.15915494, v45
	v_cos_f32_e32 v55, v45
	v_sin_f32_e32 v45, v45
	v_mul_f32_e32 v50, v44, v50
	v_mul_f32_e32 v51, v44, v51
	v_mul_f32_e32 v52, v44, v52
	s_waitcnt lgkmcnt(0)
	v_mul_f32_e32 v45, v45, v54
	v_cndmask_b32_e64 v45, v45, -v45, s[6:7]
	v_mul_f32_e32 v54, v83, v47
	v_fmac_f32_e32 v45, v55, v53
	v_mul_f32_e32 v55, 0.15915494, v54
	v_rndne_f32_e32 v55, v55
	v_fmac_f32_e32 v54, 0xc0c90000, v55
	v_mul_f32_e32 v53, v35, v48
	v_fmac_f32_e32 v54, 0xbafdaa22, v55
	ds_bpermute_b32 v48, v92, v53
	v_mul_f32_e32 v54, 0.15915494, v54
	v_cos_f32_e32 v55, v54
	v_sin_f32_e32 v54, v54
	v_mul_f32_e32 v52, v39, v52
	v_mul_f32_e32 v43, v44, v43
	v_mul_f32_e32 v43, v40, v43
	s_waitcnt lgkmcnt(0)
	v_mul_f32_e32 v48, v54, v48
	v_cndmask_b32_e64 v48, v48, -v48, s[6:7]
	v_mul_f32_e32 v54, v84, v47
	v_fmac_f32_e32 v48, v55, v53
	v_mul_f32_e32 v55, 0.15915494, v54
	v_rndne_f32_e32 v55, v55
	v_fmac_f32_e32 v54, 0xc0c90000, v55
	v_mul_f32_e32 v53, v36, v49
	v_fmac_f32_e32 v54, 0xbafdaa22, v55
	ds_bpermute_b32 v49, v92, v53
	v_mul_f32_e32 v54, 0.15915494, v54
	v_cos_f32_e32 v55, v54
	v_sin_f32_e32 v54, v54
	v_mul_f32_e32 v42, v44, v42
	v_mul_f32_e32 v44, v89, v47
	v_mul_f32_e32 v42, v41, v42
	s_waitcnt lgkmcnt(0)
	v_mul_f32_e32 v49, v54, v49
	v_cndmask_b32_e64 v49, v49, -v49, s[6:7]
	v_mul_f32_e32 v54, v85, v47
	v_fmac_f32_e32 v49, v55, v53
	v_mul_f32_e32 v55, 0.15915494, v54
	v_rndne_f32_e32 v55, v55
	v_fmac_f32_e32 v54, 0xc0c90000, v55
	v_mul_f32_e32 v53, v37, v50
	v_fmac_f32_e32 v54, 0xbafdaa22, v55
	ds_bpermute_b32 v50, v92, v53
	v_mul_f32_e32 v54, 0.15915494, v54
	v_cos_f32_e32 v55, v54
	v_sin_f32_e32 v54, v54
	s_waitcnt lgkmcnt(0)
	v_mul_f32_e32 v50, v54, v50
	v_cndmask_b32_e64 v50, v50, -v50, s[6:7]
	v_mul_f32_e32 v54, v86, v47
	v_fmac_f32_e32 v50, v55, v53
	v_mul_f32_e32 v55, 0.15915494, v54
	v_rndne_f32_e32 v55, v55
	v_fmac_f32_e32 v54, 0xc0c90000, v55
	v_mul_f32_e32 v53, v38, v51
	v_fmac_f32_e32 v54, 0xbafdaa22, v55
	ds_bpermute_b32 v51, v92, v53
	v_mul_f32_e32 v54, 0.15915494, v54
	v_cos_f32_e32 v55, v54
	v_sin_f32_e32 v54, v54
	s_waitcnt lgkmcnt(0)
	v_mul_f32_e32 v51, v54, v51
	v_cndmask_b32_e64 v51, v51, -v51, s[6:7]
	v_mul_f32_e32 v54, v87, v47
	v_fmac_f32_e32 v51, v55, v53
	v_mul_f32_e32 v55, 0.15915494, v54
	v_rndne_f32_e32 v55, v55
	v_fmac_f32_e32 v54, 0xc0c90000, v55
	v_fmac_f32_e32 v54, 0xbafdaa22, v55
	ds_bpermute_b32 v53, v92, v52
	v_mul_f32_e32 v54, 0.15915494, v54
	v_cos_f32_e32 v55, v54
	v_sin_f32_e32 v54, v54
	s_waitcnt lgkmcnt(0)
	v_mul_f32_e32 v53, v54, v53
	v_cndmask_b32_e64 v53, v53, -v53, s[6:7]
	v_mul_f32_e32 v54, v88, v47
	v_fmac_f32_e32 v53, v55, v52
	v_mul_f32_e32 v55, 0.15915494, v54
	v_rndne_f32_e32 v55, v55
	v_fmac_f32_e32 v54, 0xc0c90000, v55
	v_fmac_f32_e32 v54, 0xbafdaa22, v55
	ds_bpermute_b32 v52, v92, v43
	v_mul_f32_e32 v54, 0.15915494, v54
	v_cos_f32_e32 v55, v54
	v_sin_f32_e32 v54, v54
	v_mul_f32_e32 v47, 0.15915494, v44
	v_rndne_f32_e32 v47, v47
	v_fmac_f32_e32 v44, 0xc0c90000, v47
	s_waitcnt lgkmcnt(0)
	v_mul_f32_e32 v52, v54, v52
	v_cndmask_b32_e64 v52, v52, -v52, s[6:7]
	v_fmac_f32_e32 v44, 0xbafdaa22, v47
	v_fmac_f32_e32 v52, v55, v43
	ds_bpermute_b32 v43, v92, v42
	v_mul_f32_e32 v44, 0.15915494, v44
	v_cos_f32_e32 v47, v44
	v_sin_f32_e32 v44, v44
	s_waitcnt lgkmcnt(0)
	v_mul_f32_e32 v43, v44, v43
	v_cndmask_b32_e64 v54, v43, -v43, s[6:7]
	v_fmac_f32_e32 v54, v47, v42
	v_mul_f32_e32 v42, 0x3e16c740, v45
	v_mul_f32_e32 v43, 0x3e16c740, v48
	v_cvt_pk_bf16_f32 v42, v42, v43
	v_mul_f32_e32 v43, 0x3e16c740, v49
	v_mul_f32_e32 v44, 0x3e16c740, v50
	v_cvt_pk_bf16_f32 v43, v43, v44
	v_mul_f32_e32 v44, 0x3e16c740, v51
	v_mul_f32_e32 v45, 0x3e16c740, v53
	v_cvt_pk_bf16_f32 v44, v44, v45
	v_mul_f32_e32 v45, 0x3e16c740, v52
	v_lshl_add_u64 v[48:49], v[70:71], 0, v[74:75]
	v_mul_f32_e32 v47, 0x3e16c740, v54
	v_cvt_pk_bf16_f32 v45, v45, v47
	global_store_dwordx4 v[48:49], v[42:45], off
	s_and_saveexec_b64 s[0:1], s[8:9]
	s_cbranch_execz .LBB0_1451
	v_mad_u64_u32 v[46:47], s[8:9], v46, 6, v[66:67]
	v_lshlrev_b64 v[46:47], 8, v[46:47]
	v_lshl_add_u64 v[46:47], v[68:69], 0, v[46:47]
	v_lshl_add_u64 v[46:47], v[46:47], 0, v[64:65]
	global_store_dwordx4 v[46:47], v[42:45], off
	s_branch .LBB0_1451
